# s5 E@U: E workspace stored fragment-major, A fragments loaded directly (coalesced, dir-0 prefetched in unit prologue), LDS staging and its two barriers removed
# speedup vs baseline: 1.0160x; 1.0010x over previous
.LBB0_45:
	v_bfe_u32 v4, v2, 4, 4
	s_movk_i32 s24, 0x1000
	v_ashrrev_i32_e32 v16, 5, v3
	v_cmp_gt_u32_e32 vcc, s24, v3
	v_xor_b32_e32 v8, 15, v4
	v_ashrrev_i32_e32 v6, 12, v3
	v_and_b32_e32 v7, 63, v16
	v_cndmask_b32_e32 v4, v4, v8, vcc
	v_mad_i32_i24 v4, v6, 17, v4
	v_lshlrev_b32_e32 v8, 2, v7
	v_lshl_or_b32 v4, v4, 8, v8
	v_add_u32_e32 v4, 0, v4
	v_and_b32_e32 v5, 8, v2
	ds_read2st64_b32 v[18:19], v4 offset1:34
	v_lshlrev_b32_e32 v4, 10, v6
	v_lshlrev_b32_e32 v6, 4, v7
	v_or3_b32 v4, v6, v4, v5
	v_and_b32_e32 v5, 0x800, v3
	v_lshl_add_u32 v17, v4, 2, 0
	v_cmp_eq_u32_e32 vcc, 0, v5
	ds_read_b128 v[4:7], v17 offset:17408
	ds_read_b128 v[8:11], v17 offset:17424
	ds_read_b128 v[12:15], v17 offset:25600
	s_waitcnt lgkmcnt(3)
	v_mov_b32_e32 v20, v19
	v_mov_b32_e32 v21, v18
	s_waitcnt lgkmcnt(2)
	v_mov_b32_e32 v22, v4
	v_and_b32_e32 v26, 0xf8, v2
	s_waitcnt lgkmcnt(0)
	v_mov_b32_e32 v23, v12
	v_pk_mul_f32 v[24:25], v[20:21], v[22:23]
	v_pk_mul_f32 v[22:23], v[18:19], v[22:23]
	v_add_f32_e32 v4, v24, v25
	v_sub_f32_e32 v12, v22, v23
	v_cndmask_b32_e32 v22, v4, v12, vcc
	v_mov_b32_e32 v12, v5
	v_pk_mul_f32 v[4:5], v[20:21], v[12:13]
	v_lshlrev_b32_e32 v66, 1, v26
	v_add_f32_e32 v23, v4, v5
	v_pk_mul_f32 v[4:5], v[18:19], v[12:13]
	v_add_u32_e32 v2, 0x1000, v2
	v_sub_f32_e32 v4, v4, v5
	v_cndmask_b32_e32 v23, v23, v4, vcc
	v_mov_b32_e32 v4, v6
	v_mov_b32_e32 v5, v14
	v_pk_mul_f32 v[12:13], v[20:21], v[4:5]
	v_pk_mul_f32 v[4:5], v[18:19], v[4:5]
	v_add_f32_e32 v6, v12, v13
	v_sub_f32_e32 v4, v4, v5
	v_mov_b32_e32 v14, v7
	v_cndmask_b32_e32 v24, v6, v4, vcc
	v_pk_mul_f32 v[4:5], v[20:21], v[14:15]
	v_mov_b32_e32 v12, v8
	v_add_f32_e32 v6, v4, v5
	v_pk_mul_f32 v[4:5], v[18:19], v[14:15]
	s_nop 0
	v_sub_f32_e32 v4, v4, v5
	v_cndmask_b32_e32 v25, v6, v4, vcc
	ds_read_b128 v[4:7], v17 offset:25616
	v_ashrrev_i32_e32 v17, 31, v16
	s_waitcnt lgkmcnt(0)
	v_mov_b32_e32 v13, v4
	v_pk_mul_f32 v[14:15], v[20:21], v[12:13]
	v_pk_mul_f32 v[12:13], v[18:19], v[12:13]
	v_add_f32_e32 v4, v14, v15
	v_sub_f32_e32 v8, v12, v13
	v_cndmask_b32_e32 v12, v4, v8, vcc
	v_mov_b32_e32 v4, v9
	v_pk_mul_f32 v[8:9], v[20:21], v[4:5]
	v_pk_mul_f32 v[4:5], v[18:19], v[4:5]
	v_add_f32_e32 v8, v8, v9
	v_sub_f32_e32 v4, v4, v5
	v_cndmask_b32_e32 v13, v8, v4, vcc
	v_mov_b32_e32 v4, v10
	v_mov_b32_e32 v5, v6
	v_pk_mul_f32 v[8:9], v[20:21], v[4:5]
	v_pk_mul_f32 v[4:5], v[18:19], v[4:5]
	v_add_f32_e32 v6, v8, v9
	v_sub_f32_e32 v4, v4, v5
	v_cndmask_b32_e32 v8, v6, v4, vcc
	v_mov_b32_e32 v6, v11
	v_pk_mul_f32 v[4:5], v[20:21], v[6:7]
	s_nop 0
	v_add_f32_e32 v9, v4, v5
	v_pk_mul_f32 v[4:5], v[18:19], v[6:7]
	v_cvt_pk_bf16_f32 v6, v12, v13
	s_nop 0
	v_sub_f32_e32 v4, v4, v5
	v_cndmask_b32_e32 v7, v9, v4, vcc
	v_cvt_pk_bf16_f32 v7, v8, v7
	v_lshrrev_b32_e32 v8, 5, v16
	v_lshlrev_b32_e32 v8, 14, v8
	v_and_b32_e32 v9, 31, v16
	v_lshl_add_u32 v8, v9, 5, v8
	v_lshrrev_b32_e32 v9, 4, v26
	v_lshl_add_u32 v8, v9, 10, v8
	v_and_b32_e32 v9, 8, v26
	v_lshl_add_u32 v8, v9, 1, v8
	v_mov_b32_e32 v9, 0
	v_lshl_add_u64 v[8:9], s[20:21], 0, v[8:9]
	v_cvt_pk_bf16_f32 v4, v22, v23
	v_cvt_pk_bf16_f32 v5, v24, v25
	global_store_dwordx4 v[8:9], v[4:7], off
	v_cmp_lt_i32_e32 vcc, s96, v3
	s_or_b64 s[22:23], vcc, s[22:23]
	v_add_u32_e32 v4, 0x200, v3
	v_mov_b32_e32 v3, v4
	s_andn2_b64 exec, exec, s[22:23]
	s_cbranch_execnz .LBB0_45

.LBB0_718:
	s_and_b32 s7, s17, 31
	s_add_i32 s88, s16, s7
	s_and_b32 s23, s6, 31
	s_lshl_b64 s[8:9], s[88:89], 18
	s_or_b32 s88, s23, s16
	s_ashr_i32 s7, s6, 31
	s_lshl_b64 s[10:11], s[88:89], 18
	s_lshl_b64 s[24:25], s[6:7], 16
	s_add_u32 s24, s12, s24
	s_addc_u32 s25, s13, s25
	v_lshl_add_u64 v[0:1], s[24:25], 0, v[120:121]
	s_barrier
	global_load_dwordx4 v[0:3], v[0:1], off
	v_lshl_add_u64 v[4:5], s[24:25], 0, v[122:123]
	global_load_dwordx4 v[4:7], v[4:5], off
	v_lshl_add_u64 v[8:9], s[24:25], 0, v[124:125]
	global_load_dwordx4 v[8:11], v[8:9], off
	v_lshl_add_u64 v[12:13], s[24:25], 0, v[126:127]
	global_load_dwordx4 v[12:15], v[12:13], off
	v_lshl_add_u64 v[16:17], s[24:25], 0, v[128:129]
	global_load_dwordx4 v[16:19], v[16:17], off
	v_lshl_add_u64 v[20:21], s[24:25], 0, v[130:131]
	global_load_dwordx4 v[20:23], v[20:21], off
	v_lshl_add_u64 v[24:25], s[24:25], 0, v[132:133]
	global_load_dwordx4 v[24:27], v[24:25], off
	v_lshl_add_u64 v[28:29], s[24:25], 0, v[134:135]
	global_load_dwordx4 v[28:31], v[28:29], off
	v_mov_b32_e32 v32, v33
	v_mov_b32_e32 v46, v33
	v_mov_b32_e32 v47, v33
	s_lshl_b64 s[24:25], s[88:89], 17
	s_waitcnt vmcnt(12)
	v_mov_b32_e32 v34, v33
	v_mov_b32_e32 v35, v33
	v_mov_b32_e32 v36, v33
	v_mov_b32_e32 v37, v33
	s_waitcnt vmcnt(12)
	v_mov_b32_e32 v38, v33
	v_mov_b32_e32 v39, v33
	v_mov_b32_e32 v40, v33
	v_mov_b32_e32 v41, v33
	v_mov_b32_e32 v42, v33
	v_mov_b32_e32 v43, v33
	v_mov_b32_e32 v44, v33
	v_mov_b32_e32 v45, v33
	s_waitcnt vmcnt(10)
	v_mov_b64_e32 v[78:79], v[46:47]
	v_mov_b64_e32 v[62:63], v[46:47]
	v_lshl_add_u64 v[148:149], v[112:113], 0, s[10:11]
	v_lshl_add_u64 v[150:151], v[116:117], 0, s[24:25]
	v_lshl_add_u32 v147, s88, 8, v143
	v_lshl_add_u64 v[152:153], v[144:145], 0, s[8:9]
	s_mov_b32 s88, 0
	v_lshrrev_b32_e32 v247, 5, v119
	v_and_b32_e32 v246, 31, v119
	v_lshlrev_b32_e32 v246, 5, v246
	v_lshl_add_u32 v246, v247, 14, v246
	v_add_u32_e32 v246, 0x1000, v246
	v_mov_b32_e32 v247, v33
	v_lshl_add_u64 v[246:247], v[150:151], 0, v[246:247]
	global_load_dwordx4 v[166:169], v[246:247], off offset:-4096
	global_load_dwordx4 v[170:173], v[246:247], off offset:-3072
	global_load_dwordx4 v[174:177], v[246:247], off offset:-2048
	global_load_dwordx4 v[190:193], v[246:247], off offset:-1024
	global_load_dwordx4 v[194:197], v[246:247], off offset:0
	global_load_dwordx4 v[198:201], v[246:247], off offset:1024
	global_load_dwordx4 v[202:205], v[246:247], off offset:2048
	global_load_dwordx4 v[206:209], v[246:247], off offset:3072
	s_mov_b64 s[10:11], -1
	v_mov_b64_e32 v[76:77], v[44:45]
	v_mov_b64_e32 v[74:75], v[42:43]
	v_mov_b64_e32 v[72:73], v[40:41]
	v_mov_b64_e32 v[70:71], v[38:39]
	v_mov_b64_e32 v[68:69], v[36:37]
	v_mov_b64_e32 v[66:67], v[34:35]
	v_mov_b64_e32 v[64:65], v[32:33]
	v_mov_b64_e32 v[60:61], v[44:45]
	v_mov_b64_e32 v[58:59], v[42:43]
	v_mov_b64_e32 v[56:57], v[40:41]
	v_mov_b64_e32 v[54:55], v[38:39]
	v_mov_b64_e32 v[52:53], v[36:37]
	v_mov_b64_e32 v[50:51], v[34:35]
	v_mov_b64_e32 v[48:49], v[32:33]
	s_waitcnt vmcnt(15)
	ds_write_b128 v157, v[0:3]
	s_waitcnt vmcnt(14)
	ds_write_b128 v158, v[4:7]
	s_waitcnt vmcnt(13)
	ds_write_b128 v159, v[8:11]
	s_waitcnt vmcnt(12)
	ds_write_b128 v160, v[12:15]
	s_waitcnt vmcnt(11)
	ds_write_b128 v161, v[16:19]
	s_waitcnt vmcnt(10)
	ds_write_b128 v162, v[20:23]
	s_waitcnt vmcnt(9)
	ds_write_b128 v163, v[24:27]
	s_waitcnt vmcnt(8)
	ds_write_b128 v164, v[28:31]
	v_mov_b64_e32 v[16:17], v[32:33]
	v_mov_b64_e32 v[0:1], v[32:33]
	v_mov_b64_e32 v[18:19], v[34:35]
	v_mov_b64_e32 v[20:21], v[36:37]
	v_mov_b64_e32 v[22:23], v[38:39]
	v_mov_b64_e32 v[24:25], v[40:41]
	v_mov_b64_e32 v[26:27], v[42:43]
	v_mov_b64_e32 v[28:29], v[44:45]
	v_mov_b64_e32 v[30:31], v[46:47]
	v_mov_b64_e32 v[2:3], v[34:35]
	v_mov_b64_e32 v[4:5], v[36:37]
	v_mov_b64_e32 v[6:7], v[38:39]
	v_mov_b64_e32 v[8:9], v[40:41]
	v_mov_b64_e32 v[10:11], v[42:43]
	v_mov_b64_e32 v[12:13], v[44:45]
	v_mov_b64_e32 v[14:15], v[46:47]
	s_waitcnt lgkmcnt(0)
	s_barrier
.LBB0_719:
	v_add_u32_e32 v34, s88, v119
	v_lshrrev_b32_e32 v35, 5, v34
	v_and_b32_e32 v34, 31, v34
	v_lshlrev_b32_e32 v34, 5, v34
	v_lshl_add_u32 v34, v35, 14, v34
	v_add_u32_e32 v34, 0x1000, v34
	v_mov_b32_e32 v35, v33
	v_lshl_add_u64 v[34:35], v[150:151], 0, v[34:35]
	v_mov_b32_e32 v44, 0x2000
	v_mov_b32_e32 v45, v33
	v_lshl_add_u64 v[44:45], v[34:35], 0, v[44:45]
	s_and_b64 s[30:31], s[10:11], exec
	s_cbranch_scc1 .Ls5_eu_early
	global_load_dwordx4 v[166:169], v[34:35], off offset:-4096
	global_load_dwordx4 v[170:173], v[34:35], off offset:-3072
	global_load_dwordx4 v[174:177], v[34:35], off offset:-2048
	global_load_dwordx4 v[190:193], v[34:35], off offset:-1024
	global_load_dwordx4 v[194:197], v[34:35], off offset:0
	global_load_dwordx4 v[198:201], v[34:35], off offset:1024
	global_load_dwordx4 v[202:205], v[34:35], off offset:2048
	global_load_dwordx4 v[206:209], v[34:35], off offset:3072
.Ls5_eu_early:
	v_add_u32_e32 v32, v139, v141
	ds_read_b128 v[246:249], v32
	ds_read_b128 v[250:253], v32 offset:16896
	ds_read_b128 v[36:39], v32 offset:32
	ds_read_b128 v[40:43], v32 offset:16928
	s_waitcnt vmcnt(7) lgkmcnt(3)
	v_mfma_f32_32x32x16_bf16 v[96:111], v[166:169], v[246:249], 0
	ds_read_b128 v[246:249], v32 offset:64
	s_waitcnt lgkmcnt(3)
	v_mfma_f32_32x32x16_bf16 v[80:95], v[166:169], v[250:253], 0
	ds_read_b128 v[250:253], v32 offset:16960
	global_load_dwordx4 v[166:169], v[44:45], off offset:-4096
	s_waitcnt vmcnt(7) lgkmcnt(3)
	v_mfma_f32_32x32x16_bf16 v[96:111], v[170:173], v[36:39], v[96:111]
	ds_read_b128 v[36:39], v32 offset:96
	s_waitcnt lgkmcnt(3)
	v_mfma_f32_32x32x16_bf16 v[80:95], v[170:173], v[40:43], v[80:95]
	ds_read_b128 v[40:43], v32 offset:16992
	global_load_dwordx4 v[170:173], v[44:45], off offset:-3072
	s_waitcnt vmcnt(7) lgkmcnt(3)
	v_mfma_f32_32x32x16_bf16 v[96:111], v[174:177], v[246:249], v[96:111]
	ds_read_b128 v[246:249], v32 offset:128
	s_waitcnt lgkmcnt(3)
	v_mfma_f32_32x32x16_bf16 v[80:95], v[174:177], v[250:253], v[80:95]
	ds_read_b128 v[250:253], v32 offset:17024
	global_load_dwordx4 v[174:177], v[44:45], off offset:-2048
	s_waitcnt vmcnt(7) lgkmcnt(3)
	v_mfma_f32_32x32x16_bf16 v[96:111], v[190:193], v[36:39], v[96:111]
	ds_read_b128 v[36:39], v32 offset:160
	s_waitcnt lgkmcnt(3)
	v_mfma_f32_32x32x16_bf16 v[80:95], v[190:193], v[40:43], v[80:95]
	ds_read_b128 v[40:43], v32 offset:17056
	global_load_dwordx4 v[190:193], v[44:45], off offset:-1024
	s_waitcnt vmcnt(7) lgkmcnt(3)
	v_mfma_f32_32x32x16_bf16 v[96:111], v[194:197], v[246:249], v[96:111]
	ds_read_b128 v[246:249], v32 offset:192
	s_waitcnt lgkmcnt(3)
	v_mfma_f32_32x32x16_bf16 v[80:95], v[194:197], v[250:253], v[80:95]
	ds_read_b128 v[250:253], v32 offset:17088
	global_load_dwordx4 v[194:197], v[44:45], off offset:0
	s_waitcnt vmcnt(7) lgkmcnt(3)
	v_mfma_f32_32x32x16_bf16 v[96:111], v[198:201], v[36:39], v[96:111]
	ds_read_b128 v[36:39], v32 offset:224
	s_waitcnt lgkmcnt(3)
	v_mfma_f32_32x32x16_bf16 v[80:95], v[198:201], v[40:43], v[80:95]
	ds_read_b128 v[40:43], v32 offset:17120
	global_load_dwordx4 v[198:201], v[44:45], off offset:1024
	s_waitcnt vmcnt(7) lgkmcnt(3)
	v_mfma_f32_32x32x16_bf16 v[96:111], v[202:205], v[246:249], v[96:111]
	ds_read_b128 v[246:249], v32 offset:256
	s_waitcnt lgkmcnt(3)
	v_mfma_f32_32x32x16_bf16 v[80:95], v[202:205], v[250:253], v[80:95]
	ds_read_b128 v[250:253], v32 offset:17152
	global_load_dwordx4 v[202:205], v[44:45], off offset:2048
	s_waitcnt vmcnt(7) lgkmcnt(3)
	v_mfma_f32_32x32x16_bf16 v[96:111], v[206:209], v[36:39], v[96:111]
	ds_read_b128 v[36:39], v32 offset:288
	s_waitcnt lgkmcnt(3)
	v_mfma_f32_32x32x16_bf16 v[80:95], v[206:209], v[40:43], v[80:95]
	ds_read_b128 v[40:43], v32 offset:17184
	global_load_dwordx4 v[206:209], v[44:45], off offset:3072
	s_waitcnt vmcnt(7) lgkmcnt(3)
	v_mfma_f32_32x32x16_bf16 v[96:111], v[166:169], v[246:249], v[96:111]
	ds_read_b128 v[246:249], v32 offset:320
	s_waitcnt lgkmcnt(3)
	v_mfma_f32_32x32x16_bf16 v[80:95], v[166:169], v[250:253], v[80:95]
	ds_read_b128 v[250:253], v32 offset:17216
	s_waitcnt vmcnt(6) lgkmcnt(3)
	v_mfma_f32_32x32x16_bf16 v[96:111], v[170:173], v[36:39], v[96:111]
	ds_read_b128 v[36:39], v32 offset:352
	s_waitcnt lgkmcnt(3)
	v_mfma_f32_32x32x16_bf16 v[80:95], v[170:173], v[40:43], v[80:95]
	ds_read_b128 v[40:43], v32 offset:17248
	s_waitcnt vmcnt(5) lgkmcnt(3)
	v_mfma_f32_32x32x16_bf16 v[96:111], v[174:177], v[246:249], v[96:111]
	ds_read_b128 v[246:249], v32 offset:384
	s_waitcnt lgkmcnt(3)
	v_mfma_f32_32x32x16_bf16 v[80:95], v[174:177], v[250:253], v[80:95]
	ds_read_b128 v[250:253], v32 offset:17280
	s_waitcnt vmcnt(4) lgkmcnt(3)
	v_mfma_f32_32x32x16_bf16 v[96:111], v[190:193], v[36:39], v[96:111]
	ds_read_b128 v[36:39], v32 offset:416
	s_waitcnt lgkmcnt(3)
	v_mfma_f32_32x32x16_bf16 v[80:95], v[190:193], v[40:43], v[80:95]
	ds_read_b128 v[40:43], v32 offset:17312
	s_waitcnt vmcnt(3) lgkmcnt(3)
	v_mfma_f32_32x32x16_bf16 v[96:111], v[194:197], v[246:249], v[96:111]
	ds_read_b128 v[246:249], v32 offset:448
	s_waitcnt lgkmcnt(3)
	v_mfma_f32_32x32x16_bf16 v[80:95], v[194:197], v[250:253], v[80:95]
	ds_read_b128 v[250:253], v32 offset:17344
	s_waitcnt vmcnt(2) lgkmcnt(3)
	v_mfma_f32_32x32x16_bf16 v[96:111], v[198:201], v[36:39], v[96:111]
	ds_read_b128 v[36:39], v32 offset:480
	s_waitcnt lgkmcnt(3)
	v_mfma_f32_32x32x16_bf16 v[80:95], v[198:201], v[40:43], v[80:95]
	ds_read_b128 v[40:43], v32 offset:17376
	s_waitcnt vmcnt(1) lgkmcnt(3)
	v_mfma_f32_32x32x16_bf16 v[96:111], v[202:205], v[246:249], v[96:111]
	s_waitcnt lgkmcnt(2)
	v_mfma_f32_32x32x16_bf16 v[80:95], v[202:205], v[250:253], v[80:95]
	s_waitcnt vmcnt(0) lgkmcnt(1)
	v_mfma_f32_32x32x16_bf16 v[96:111], v[206:209], v[36:39], v[96:111]
	s_waitcnt lgkmcnt(0)
	v_mfma_f32_32x32x16_bf16 v[80:95], v[206:209], v[40:43], v[80:95]
	s_nop 15
	ds_write_b128 v165, v[96:99]
	ds_write_b128 v165, v[100:103] offset:32
	ds_write_b128 v165, v[104:107] offset:64
	ds_write_b128 v165, v[108:111] offset:96
	ds_write_b128 v165, v[80:83] offset:16896
	ds_write_b128 v165, v[84:87] offset:16928
	ds_write_b128 v165, v[88:91] offset:16960
	ds_write_b128 v165, v[92:95] offset:16992
	s_waitcnt lgkmcnt(0)
	s_barrier
	s_and_b64 s[30:31], s[10:11], exec
	s_cbranch_scc0 .Ls5_nopf
	v_mov_b32_e32 v34, 0x2000
	v_mov_b32_e32 v35, v33
	v_lshl_add_u64 v[34:35], v[148:149], 0, v[34:35]
	global_load_dwordx4 v[100:103], v[148:149], off offset:-4096
	global_load_dwordx4 v[104:107], v[148:149], off offset:-3072
	global_load_dwordx4 v[108:111], v[148:149], off offset:-2048
	global_load_dwordx4 v[166:169], v[148:149], off offset:-1024
	global_load_dwordx4 v[170:173], v[148:149], off offset:0
	global_load_dwordx4 v[174:177], v[148:149], off offset:1024
	global_load_dwordx4 v[190:193], v[148:149], off offset:2048
	global_load_dwordx4 v[194:197], v[148:149], off offset:3072
	global_load_dwordx4 v[198:201], v[34:35], off offset:-4096
	global_load_dwordx4 v[202:205], v[34:35], off offset:-3072
	global_load_dwordx4 v[206:209], v[34:35], off offset:-2048
	global_load_dwordx4 v[234:237], v[34:35], off offset:-1024
	global_load_dwordx4 v[238:241], v[34:35], off offset:0
	global_load_dwordx4 v[242:245], v[34:35], off offset:1024
	global_load_dwordx4 v[246:249], v[34:35], off offset:2048
	global_load_dwordx4 v[250:253], v[34:35], off offset:3072
